# G5 epilogue: hidden-activation stores (full 128-B segments now) marked nt
# speedup vs baseline: 1.0281x; 1.0036x over previous
.LBB0_241:
	s_or_b64 exec, exec, s[0:1]
	v_add_u32_e32 v131, v130, v172
	ds_read_b128 v[132:135], v131
	ds_read_b128 v[142:145], v131 offset:4096
	ds_read_b128 v[146:149], v131 offset:8192
	ds_read_b128 v[150:153], v131 offset:12288
	v_xad_u32 v131, v172, v233, v128
	ds_read_b128 v[154:157], v131 offset:32768
	v_xor_b32_e32 v230, 0x80, v131
	ds_read_b128 v[158:161], v230 offset:32768
	s_setprio 1
	s_waitcnt lgkmcnt(0)
	v_mfma_f32_32x32x16_bf16 v[112:127], v[132:135], v[154:157], v[112:127]
	v_mfma_f32_32x32x16_bf16 v[96:111], v[132:135], v[158:161], v[96:111]
	v_mfma_f32_32x32x16_bf16 v[80:95], v[142:145], v[154:157], v[80:95]
	v_mfma_f32_32x32x16_bf16 v[64:79], v[142:145], v[158:161], v[64:79]
	v_mfma_f32_32x32x16_bf16 v[48:63], v[146:149], v[154:157], v[48:63]
	v_mfma_f32_32x32x16_bf16 v[32:47], v[146:149], v[158:161], v[32:47]
	v_mfma_f32_32x32x16_bf16 v[16:31], v[150:153], v[154:157], v[16:31]
	v_mfma_f32_32x32x16_bf16 v[0:15], v[150:153], v[158:161], v[0:15]
	s_setprio 0
	v_add_u32_e32 v141, v130, v171
	ds_read_b128 v[130:133], v141
	ds_read_b128 v[134:137], v141 offset:4096
	ds_read_b128 v[142:145], v141 offset:8192
	ds_read_b128 v[146:149], v141 offset:12288
	v_xad_u32 v128, v171, v233, v128
	ds_read_b128 v[150:153], v128 offset:32768
	v_xor_b32_e32 v230, 0x80, v128
	ds_read_b128 v[154:157], v230 offset:32768
	s_setprio 1
	s_waitcnt lgkmcnt(0)
	v_mfma_f32_32x32x16_bf16 v[112:127], v[130:133], v[150:153], v[112:127]
	v_mfma_f32_32x32x16_bf16 v[96:111], v[130:133], v[154:157], v[96:111]
	v_mfma_f32_32x32x16_bf16 v[80:95], v[134:137], v[150:153], v[80:95]
	v_mfma_f32_32x32x16_bf16 v[64:79], v[134:137], v[154:157], v[64:79]
	v_mfma_f32_32x32x16_bf16 v[48:63], v[142:145], v[150:153], v[48:63]
	v_mfma_f32_32x32x16_bf16 v[32:47], v[142:145], v[154:157], v[32:47]
	v_mfma_f32_32x32x16_bf16 v[16:31], v[146:149], v[150:153], v[16:31]
	v_mfma_f32_32x32x16_bf16 v[0:15], v[146:149], v[154:157], v[0:15]
	s_setprio 0
	v_add_u32_e32 v136, v170, v168
	v_and_b32_e32 v130, 31, v224
	v_and_b32_e32 v131, 0xc0, v224
	v_lshl_or_b32 v130, v130, 1, v131
	v_or_b32_e32 v130, v130, v169
	v_lshlrev_b32_e32 v136, 13, v136
	v_lshl_add_u32 v136, v130, 1, v136
	v_and_b32_e32 v131, 16, v224
	v_max_f32_e32 v112, v112, v112
	v_max_f32_e32 v96, v96, v96
	v_max_f32_e32 v112, 0, v112
	v_max_f32_e32 v96, 0, v96
	v_mul_f32_e32 v112, v112, v112
	v_mul_f32_e32 v96, v96, v96
	s_mov_b32 s0, s42
	s_mov_b32 s1, s43
	v_cvt_pk_bf16_f32 v112, v112, v96
	v_alignbit_b32 v112, v112, v112, v131
	global_store_dword v136, v112, s[0:1] nt
	v_max_f32_e32 v113, v113, v113
	v_max_f32_e32 v97, v97, v97
	v_max_f32_e32 v113, 0, v113
	v_max_f32_e32 v97, 0, v97
	v_mul_f32_e32 v113, v113, v113
	v_mul_f32_e32 v97, v97, v97
	s_add_u32 s0, s42, 0x2000
	s_addc_u32 s1, s43, 0
	v_cvt_pk_bf16_f32 v113, v113, v97
	v_alignbit_b32 v113, v113, v113, v131
	global_store_dword v136, v113, s[0:1] nt
	v_max_f32_e32 v114, v114, v114
	v_max_f32_e32 v98, v98, v98
	v_max_f32_e32 v114, 0, v114
	v_max_f32_e32 v98, 0, v98
	v_mul_f32_e32 v114, v114, v114
	v_mul_f32_e32 v98, v98, v98
	s_add_u32 s0, s42, 0x4000
	s_addc_u32 s1, s43, 0
	v_cvt_pk_bf16_f32 v114, v114, v98
	v_alignbit_b32 v114, v114, v114, v131
	global_store_dword v136, v114, s[0:1] nt
	v_max_f32_e32 v115, v115, v115
	v_max_f32_e32 v99, v99, v99
	v_max_f32_e32 v115, 0, v115
	v_max_f32_e32 v99, 0, v99
	v_mul_f32_e32 v115, v115, v115
	v_mul_f32_e32 v99, v99, v99
	s_add_u32 s0, s42, 0x6000
	s_addc_u32 s1, s43, 0
	v_cvt_pk_bf16_f32 v115, v115, v99
	v_alignbit_b32 v115, v115, v115, v131
	global_store_dword v136, v115, s[0:1] nt
	v_max_f32_e32 v116, v116, v116
	v_max_f32_e32 v100, v100, v100
	v_max_f32_e32 v116, 0, v116
	v_max_f32_e32 v100, 0, v100
	v_mul_f32_e32 v116, v116, v116
	v_mul_f32_e32 v100, v100, v100
	s_add_u32 s0, s42, 0x10000
	s_addc_u32 s1, s43, 0
	v_cvt_pk_bf16_f32 v116, v116, v100
	v_alignbit_b32 v116, v116, v116, v131
	global_store_dword v136, v116, s[0:1] nt
	v_max_f32_e32 v117, v117, v117
	v_max_f32_e32 v101, v101, v101
	v_max_f32_e32 v117, 0, v117
	v_max_f32_e32 v101, 0, v101
	v_mul_f32_e32 v117, v117, v117
	v_mul_f32_e32 v101, v101, v101
	s_add_u32 s0, s42, 0x12000
	s_addc_u32 s1, s43, 0
	v_cvt_pk_bf16_f32 v117, v117, v101
	v_alignbit_b32 v117, v117, v117, v131
	global_store_dword v136, v117, s[0:1] nt
	v_max_f32_e32 v118, v118, v118
	v_max_f32_e32 v102, v102, v102
	v_max_f32_e32 v118, 0, v118
	v_max_f32_e32 v102, 0, v102
	v_mul_f32_e32 v118, v118, v118
	v_mul_f32_e32 v102, v102, v102
	s_add_u32 s0, s42, 0x14000
	s_addc_u32 s1, s43, 0
	v_cvt_pk_bf16_f32 v118, v118, v102
	v_alignbit_b32 v118, v118, v118, v131
	global_store_dword v136, v118, s[0:1] nt
	v_max_f32_e32 v119, v119, v119
	v_max_f32_e32 v103, v103, v103
	v_max_f32_e32 v119, 0, v119
	v_max_f32_e32 v103, 0, v103
	v_mul_f32_e32 v119, v119, v119
	v_mul_f32_e32 v103, v103, v103
	s_add_u32 s0, s42, 0x16000
	s_addc_u32 s1, s43, 0
	v_cvt_pk_bf16_f32 v119, v119, v103
	v_alignbit_b32 v119, v119, v119, v131
	global_store_dword v136, v119, s[0:1] nt
	v_max_f32_e32 v120, v120, v120
	v_max_f32_e32 v104, v104, v104
	v_max_f32_e32 v120, 0, v120
	v_max_f32_e32 v104, 0, v104
	v_mul_f32_e32 v120, v120, v120
	v_mul_f32_e32 v104, v104, v104
	s_add_u32 s0, s42, 0x20000
	s_addc_u32 s1, s43, 0
	v_cvt_pk_bf16_f32 v120, v120, v104
	v_alignbit_b32 v120, v120, v120, v131
	global_store_dword v136, v120, s[0:1] nt
	v_max_f32_e32 v121, v121, v121
	v_max_f32_e32 v105, v105, v105
	v_max_f32_e32 v121, 0, v121
	v_max_f32_e32 v105, 0, v105
	v_mul_f32_e32 v121, v121, v121
	v_mul_f32_e32 v105, v105, v105
	s_add_u32 s0, s42, 0x22000
	s_addc_u32 s1, s43, 0
	v_cvt_pk_bf16_f32 v121, v121, v105
	v_alignbit_b32 v121, v121, v121, v131
	global_store_dword v136, v121, s[0:1] nt
	v_max_f32_e32 v122, v122, v122
	v_max_f32_e32 v106, v106, v106
	v_max_f32_e32 v122, 0, v122
	v_max_f32_e32 v106, 0, v106
	v_mul_f32_e32 v122, v122, v122
	v_mul_f32_e32 v106, v106, v106
	s_add_u32 s0, s42, 0x24000
	s_addc_u32 s1, s43, 0
	v_cvt_pk_bf16_f32 v122, v122, v106
	v_alignbit_b32 v122, v122, v122, v131
	global_store_dword v136, v122, s[0:1] nt
	v_max_f32_e32 v123, v123, v123
	v_max_f32_e32 v107, v107, v107
	v_max_f32_e32 v123, 0, v123
	v_max_f32_e32 v107, 0, v107
	v_mul_f32_e32 v123, v123, v123
	v_mul_f32_e32 v107, v107, v107
	s_add_u32 s0, s42, 0x26000
	s_addc_u32 s1, s43, 0
	v_cvt_pk_bf16_f32 v123, v123, v107
	v_alignbit_b32 v123, v123, v123, v131
	global_store_dword v136, v123, s[0:1] nt
	v_max_f32_e32 v124, v124, v124
	v_max_f32_e32 v108, v108, v108
	v_max_f32_e32 v124, 0, v124
	v_max_f32_e32 v108, 0, v108
	v_mul_f32_e32 v124, v124, v124
	v_mul_f32_e32 v108, v108, v108
	s_add_u32 s0, s42, 0x30000
	s_addc_u32 s1, s43, 0
	v_cvt_pk_bf16_f32 v124, v124, v108
	v_alignbit_b32 v124, v124, v124, v131
	global_store_dword v136, v124, s[0:1] nt
	v_max_f32_e32 v125, v125, v125
	v_max_f32_e32 v109, v109, v109
	v_max_f32_e32 v125, 0, v125
	v_max_f32_e32 v109, 0, v109
	v_mul_f32_e32 v125, v125, v125
	v_mul_f32_e32 v109, v109, v109
	s_add_u32 s0, s42, 0x32000
	s_addc_u32 s1, s43, 0
	v_cvt_pk_bf16_f32 v125, v125, v109
	v_alignbit_b32 v125, v125, v125, v131
	global_store_dword v136, v125, s[0:1] nt
	v_max_f32_e32 v126, v126, v126
	v_max_f32_e32 v110, v110, v110
	v_max_f32_e32 v126, 0, v126
	v_max_f32_e32 v110, 0, v110
	v_mul_f32_e32 v126, v126, v126
	v_mul_f32_e32 v110, v110, v110
	s_add_u32 s0, s42, 0x34000
	s_addc_u32 s1, s43, 0
	v_cvt_pk_bf16_f32 v126, v126, v110
	v_alignbit_b32 v126, v126, v126, v131
	global_store_dword v136, v126, s[0:1] nt
	v_max_f32_e32 v127, v127, v127
	v_max_f32_e32 v111, v111, v111
	v_max_f32_e32 v127, 0, v127
	v_max_f32_e32 v111, 0, v111
	v_mul_f32_e32 v127, v127, v127
	v_mul_f32_e32 v111, v111, v111
	s_add_u32 s0, s42, 0x36000
	s_addc_u32 s1, s43, 0
	v_cvt_pk_bf16_f32 v127, v127, v111
	v_alignbit_b32 v127, v127, v127, v131
	global_store_dword v136, v127, s[0:1] nt
	v_max_f32_e32 v80, v80, v80
	v_max_f32_e32 v64, v64, v64
	v_max_f32_e32 v80, 0, v80
	v_max_f32_e32 v64, 0, v64
	v_mul_f32_e32 v80, v80, v80
	v_mul_f32_e32 v64, v64, v64
	s_add_u32 s0, s42, 0x40000
	s_addc_u32 s1, s43, 0
	v_cvt_pk_bf16_f32 v80, v80, v64
	v_alignbit_b32 v80, v80, v80, v131
	global_store_dword v136, v80, s[0:1] nt
	v_max_f32_e32 v81, v81, v81
	v_max_f32_e32 v65, v65, v65
	v_max_f32_e32 v81, 0, v81
	v_max_f32_e32 v65, 0, v65
	v_mul_f32_e32 v81, v81, v81
	v_mul_f32_e32 v65, v65, v65
	s_add_u32 s0, s42, 0x42000
	s_addc_u32 s1, s43, 0
	v_cvt_pk_bf16_f32 v81, v81, v65
	v_alignbit_b32 v81, v81, v81, v131
	global_store_dword v136, v81, s[0:1] nt
	v_max_f32_e32 v82, v82, v82
	v_max_f32_e32 v66, v66, v66
	v_max_f32_e32 v82, 0, v82
	v_max_f32_e32 v66, 0, v66
	v_mul_f32_e32 v82, v82, v82
	v_mul_f32_e32 v66, v66, v66
	s_add_u32 s0, s42, 0x44000
	s_addc_u32 s1, s43, 0
	v_cvt_pk_bf16_f32 v82, v82, v66
	v_alignbit_b32 v82, v82, v82, v131
	global_store_dword v136, v82, s[0:1] nt
	v_max_f32_e32 v83, v83, v83
	v_max_f32_e32 v67, v67, v67
	v_max_f32_e32 v83, 0, v83
	v_max_f32_e32 v67, 0, v67
	v_mul_f32_e32 v83, v83, v83
	v_mul_f32_e32 v67, v67, v67
	s_add_u32 s0, s42, 0x46000
	s_addc_u32 s1, s43, 0
	v_cvt_pk_bf16_f32 v83, v83, v67
	v_alignbit_b32 v83, v83, v83, v131
	global_store_dword v136, v83, s[0:1] nt
	v_max_f32_e32 v84, v84, v84
	v_max_f32_e32 v68, v68, v68
	v_max_f32_e32 v84, 0, v84
	v_max_f32_e32 v68, 0, v68
	v_mul_f32_e32 v84, v84, v84
	v_mul_f32_e32 v68, v68, v68
	s_add_u32 s0, s42, 0x50000
	s_addc_u32 s1, s43, 0
	v_cvt_pk_bf16_f32 v84, v84, v68
	v_alignbit_b32 v84, v84, v84, v131
	global_store_dword v136, v84, s[0:1] nt
	v_max_f32_e32 v85, v85, v85
	v_max_f32_e32 v69, v69, v69
	v_max_f32_e32 v85, 0, v85
	v_max_f32_e32 v69, 0, v69
	v_mul_f32_e32 v85, v85, v85
	v_mul_f32_e32 v69, v69, v69
	s_add_u32 s0, s42, 0x52000
	s_addc_u32 s1, s43, 0
	v_cvt_pk_bf16_f32 v85, v85, v69
	v_alignbit_b32 v85, v85, v85, v131
	global_store_dword v136, v85, s[0:1] nt
	v_max_f32_e32 v86, v86, v86
	v_max_f32_e32 v70, v70, v70
	v_max_f32_e32 v86, 0, v86
	v_max_f32_e32 v70, 0, v70
	v_mul_f32_e32 v86, v86, v86
	v_mul_f32_e32 v70, v70, v70
	s_add_u32 s0, s42, 0x54000
	s_addc_u32 s1, s43, 0
	v_cvt_pk_bf16_f32 v86, v86, v70
	v_alignbit_b32 v86, v86, v86, v131
	global_store_dword v136, v86, s[0:1] nt
	v_max_f32_e32 v87, v87, v87
	v_max_f32_e32 v71, v71, v71
	v_max_f32_e32 v87, 0, v87
	v_max_f32_e32 v71, 0, v71
	v_mul_f32_e32 v87, v87, v87
	v_mul_f32_e32 v71, v71, v71
	s_add_u32 s0, s42, 0x56000
	s_addc_u32 s1, s43, 0
	v_cvt_pk_bf16_f32 v87, v87, v71
	v_alignbit_b32 v87, v87, v87, v131
	global_store_dword v136, v87, s[0:1] nt
	v_max_f32_e32 v88, v88, v88
	v_max_f32_e32 v72, v72, v72
	v_max_f32_e32 v88, 0, v88
	v_max_f32_e32 v72, 0, v72
	v_mul_f32_e32 v88, v88, v88
	v_mul_f32_e32 v72, v72, v72
	s_add_u32 s0, s42, 0x60000
	s_addc_u32 s1, s43, 0
	v_cvt_pk_bf16_f32 v88, v88, v72
	v_alignbit_b32 v88, v88, v88, v131
	global_store_dword v136, v88, s[0:1] nt
	v_max_f32_e32 v89, v89, v89
	v_max_f32_e32 v73, v73, v73
	v_max_f32_e32 v89, 0, v89
	v_max_f32_e32 v73, 0, v73
	v_mul_f32_e32 v89, v89, v89
	v_mul_f32_e32 v73, v73, v73
	s_add_u32 s0, s42, 0x62000
	s_addc_u32 s1, s43, 0
	v_cvt_pk_bf16_f32 v89, v89, v73
	v_alignbit_b32 v89, v89, v89, v131
	global_store_dword v136, v89, s[0:1] nt
	v_max_f32_e32 v90, v90, v90
	v_max_f32_e32 v74, v74, v74
	v_max_f32_e32 v90, 0, v90
	v_max_f32_e32 v74, 0, v74
	v_mul_f32_e32 v90, v90, v90
	v_mul_f32_e32 v74, v74, v74
	s_add_u32 s0, s42, 0x64000
	s_addc_u32 s1, s43, 0
	v_cvt_pk_bf16_f32 v90, v90, v74
	v_alignbit_b32 v90, v90, v90, v131
	global_store_dword v136, v90, s[0:1] nt
	v_max_f32_e32 v91, v91, v91
	v_max_f32_e32 v75, v75, v75
	v_max_f32_e32 v91, 0, v91
	v_max_f32_e32 v75, 0, v75
	v_mul_f32_e32 v91, v91, v91
	v_mul_f32_e32 v75, v75, v75
	s_add_u32 s0, s42, 0x66000
	s_addc_u32 s1, s43, 0
	v_cvt_pk_bf16_f32 v91, v91, v75
	v_alignbit_b32 v91, v91, v91, v131
	global_store_dword v136, v91, s[0:1] nt
	v_max_f32_e32 v92, v92, v92
	v_max_f32_e32 v76, v76, v76
	v_max_f32_e32 v92, 0, v92
	v_max_f32_e32 v76, 0, v76
	v_mul_f32_e32 v92, v92, v92
	v_mul_f32_e32 v76, v76, v76
	s_add_u32 s0, s42, 0x70000
	s_addc_u32 s1, s43, 0
	v_cvt_pk_bf16_f32 v92, v92, v76
	v_alignbit_b32 v92, v92, v92, v131
	global_store_dword v136, v92, s[0:1] nt
	v_max_f32_e32 v93, v93, v93
	v_max_f32_e32 v77, v77, v77
	v_max_f32_e32 v93, 0, v93
	v_max_f32_e32 v77, 0, v77
	v_mul_f32_e32 v93, v93, v93
	v_mul_f32_e32 v77, v77, v77
	s_add_u32 s0, s42, 0x72000
	s_addc_u32 s1, s43, 0
	v_cvt_pk_bf16_f32 v93, v93, v77
	v_alignbit_b32 v93, v93, v93, v131
	global_store_dword v136, v93, s[0:1] nt
	v_max_f32_e32 v94, v94, v94
	v_max_f32_e32 v78, v78, v78
	v_max_f32_e32 v94, 0, v94
	v_max_f32_e32 v78, 0, v78
	v_mul_f32_e32 v94, v94, v94
	v_mul_f32_e32 v78, v78, v78
	s_add_u32 s0, s42, 0x74000
	s_addc_u32 s1, s43, 0
	v_cvt_pk_bf16_f32 v94, v94, v78
	v_alignbit_b32 v94, v94, v94, v131
	global_store_dword v136, v94, s[0:1] nt
	v_max_f32_e32 v95, v95, v95
	v_max_f32_e32 v79, v79, v79
	v_max_f32_e32 v95, 0, v95
	v_max_f32_e32 v79, 0, v79
	v_mul_f32_e32 v95, v95, v95
	v_mul_f32_e32 v79, v79, v79
	s_add_u32 s0, s42, 0x76000
	s_addc_u32 s1, s43, 0
	v_cvt_pk_bf16_f32 v95, v95, v79
	v_alignbit_b32 v95, v95, v95, v131
	global_store_dword v136, v95, s[0:1] nt
	v_max_f32_e32 v48, v48, v48
	v_max_f32_e32 v32, v32, v32
	v_max_f32_e32 v48, 0, v48
	v_max_f32_e32 v32, 0, v32
	v_mul_f32_e32 v48, v48, v48
	v_mul_f32_e32 v32, v32, v32
	s_add_u32 s0, s42, 0x80000
	s_addc_u32 s1, s43, 0
	v_cvt_pk_bf16_f32 v48, v48, v32
	v_alignbit_b32 v48, v48, v48, v131
	global_store_dword v136, v48, s[0:1] nt
	v_max_f32_e32 v49, v49, v49
	v_max_f32_e32 v33, v33, v33
	v_max_f32_e32 v49, 0, v49
	v_max_f32_e32 v33, 0, v33
	v_mul_f32_e32 v49, v49, v49
	v_mul_f32_e32 v33, v33, v33
	s_add_u32 s0, s42, 0x82000
	s_addc_u32 s1, s43, 0
	v_cvt_pk_bf16_f32 v49, v49, v33
	v_alignbit_b32 v49, v49, v49, v131
	global_store_dword v136, v49, s[0:1] nt
	v_max_f32_e32 v50, v50, v50
	v_max_f32_e32 v34, v34, v34
	v_max_f32_e32 v50, 0, v50
	v_max_f32_e32 v34, 0, v34
	v_mul_f32_e32 v50, v50, v50
	v_mul_f32_e32 v34, v34, v34
	s_add_u32 s0, s42, 0x84000
	s_addc_u32 s1, s43, 0
	v_cvt_pk_bf16_f32 v50, v50, v34
	v_alignbit_b32 v50, v50, v50, v131
	global_store_dword v136, v50, s[0:1] nt
	v_max_f32_e32 v51, v51, v51
	v_max_f32_e32 v35, v35, v35
	v_max_f32_e32 v51, 0, v51
	v_max_f32_e32 v35, 0, v35
	v_mul_f32_e32 v51, v51, v51
	v_mul_f32_e32 v35, v35, v35
	s_add_u32 s0, s42, 0x86000
	s_addc_u32 s1, s43, 0
	v_cvt_pk_bf16_f32 v51, v51, v35
	v_alignbit_b32 v51, v51, v51, v131
	global_store_dword v136, v51, s[0:1] nt
	v_max_f32_e32 v52, v52, v52
	v_max_f32_e32 v36, v36, v36
	v_max_f32_e32 v52, 0, v52
	v_max_f32_e32 v36, 0, v36
	v_mul_f32_e32 v52, v52, v52
	v_mul_f32_e32 v36, v36, v36
	s_add_u32 s0, s42, 0x90000
	s_addc_u32 s1, s43, 0
	v_cvt_pk_bf16_f32 v52, v52, v36
	v_alignbit_b32 v52, v52, v52, v131
	global_store_dword v136, v52, s[0:1] nt
	v_max_f32_e32 v53, v53, v53
	v_max_f32_e32 v37, v37, v37
	v_max_f32_e32 v53, 0, v53
	v_max_f32_e32 v37, 0, v37
	v_mul_f32_e32 v53, v53, v53
	v_mul_f32_e32 v37, v37, v37
	s_add_u32 s0, s42, 0x92000
	s_addc_u32 s1, s43, 0
	v_cvt_pk_bf16_f32 v53, v53, v37
	v_alignbit_b32 v53, v53, v53, v131
	global_store_dword v136, v53, s[0:1] nt
	v_max_f32_e32 v54, v54, v54
	v_max_f32_e32 v38, v38, v38
	v_max_f32_e32 v54, 0, v54
	v_max_f32_e32 v38, 0, v38
	v_mul_f32_e32 v54, v54, v54
	v_mul_f32_e32 v38, v38, v38
	s_add_u32 s0, s42, 0x94000
	s_addc_u32 s1, s43, 0
	v_cvt_pk_bf16_f32 v54, v54, v38
	v_alignbit_b32 v54, v54, v54, v131
	global_store_dword v136, v54, s[0:1] nt
	v_max_f32_e32 v55, v55, v55
	v_max_f32_e32 v39, v39, v39
	v_max_f32_e32 v55, 0, v55
	v_max_f32_e32 v39, 0, v39
	v_mul_f32_e32 v55, v55, v55
	v_mul_f32_e32 v39, v39, v39
	s_add_u32 s0, s42, 0x96000
	s_addc_u32 s1, s43, 0
	v_cvt_pk_bf16_f32 v55, v55, v39
	v_alignbit_b32 v55, v55, v55, v131
	global_store_dword v136, v55, s[0:1] nt
	v_max_f32_e32 v56, v56, v56
	v_max_f32_e32 v40, v40, v40
	v_max_f32_e32 v56, 0, v56
	v_max_f32_e32 v40, 0, v40
	v_mul_f32_e32 v56, v56, v56
	v_mul_f32_e32 v40, v40, v40
	s_add_u32 s0, s42, 0xa0000
	s_addc_u32 s1, s43, 0
	v_cvt_pk_bf16_f32 v56, v56, v40
	v_alignbit_b32 v56, v56, v56, v131
	global_store_dword v136, v56, s[0:1] nt
	v_max_f32_e32 v57, v57, v57
	v_max_f32_e32 v41, v41, v41
	v_max_f32_e32 v57, 0, v57
	v_max_f32_e32 v41, 0, v41
	v_mul_f32_e32 v57, v57, v57
	v_mul_f32_e32 v41, v41, v41
	s_add_u32 s0, s42, 0xa2000
	s_addc_u32 s1, s43, 0
	v_cvt_pk_bf16_f32 v57, v57, v41
	v_alignbit_b32 v57, v57, v57, v131
	global_store_dword v136, v57, s[0:1] nt
	v_max_f32_e32 v58, v58, v58
	v_max_f32_e32 v42, v42, v42
	v_max_f32_e32 v58, 0, v58
	v_max_f32_e32 v42, 0, v42
	v_mul_f32_e32 v58, v58, v58
	v_mul_f32_e32 v42, v42, v42
	s_add_u32 s0, s42, 0xa4000
	s_addc_u32 s1, s43, 0
	v_cvt_pk_bf16_f32 v58, v58, v42
	v_alignbit_b32 v58, v58, v58, v131
	global_store_dword v136, v58, s[0:1] nt
	v_max_f32_e32 v59, v59, v59
	v_max_f32_e32 v43, v43, v43
	v_max_f32_e32 v59, 0, v59
	v_max_f32_e32 v43, 0, v43
	v_mul_f32_e32 v59, v59, v59
	v_mul_f32_e32 v43, v43, v43
	s_add_u32 s0, s42, 0xa6000
	s_addc_u32 s1, s43, 0
	v_cvt_pk_bf16_f32 v59, v59, v43
	v_alignbit_b32 v59, v59, v59, v131
	global_store_dword v136, v59, s[0:1] nt
	v_max_f32_e32 v60, v60, v60
	v_max_f32_e32 v44, v44, v44
	v_max_f32_e32 v60, 0, v60
	v_max_f32_e32 v44, 0, v44
	v_mul_f32_e32 v60, v60, v60
	v_mul_f32_e32 v44, v44, v44
	s_add_u32 s0, s42, 0xb0000
	s_addc_u32 s1, s43, 0
	v_cvt_pk_bf16_f32 v60, v60, v44
	v_alignbit_b32 v60, v60, v60, v131
	global_store_dword v136, v60, s[0:1] nt
	v_max_f32_e32 v61, v61, v61
	v_max_f32_e32 v45, v45, v45
	v_max_f32_e32 v61, 0, v61
	v_max_f32_e32 v45, 0, v45
	v_mul_f32_e32 v61, v61, v61
	v_mul_f32_e32 v45, v45, v45
	s_add_u32 s0, s42, 0xb2000
	s_addc_u32 s1, s43, 0
	v_cvt_pk_bf16_f32 v61, v61, v45
	v_alignbit_b32 v61, v61, v61, v131
	global_store_dword v136, v61, s[0:1] nt
	v_max_f32_e32 v62, v62, v62
	v_max_f32_e32 v46, v46, v46
	v_max_f32_e32 v62, 0, v62
	v_max_f32_e32 v46, 0, v46
	v_mul_f32_e32 v62, v62, v62
	v_mul_f32_e32 v46, v46, v46
	s_add_u32 s0, s42, 0xb4000
	s_addc_u32 s1, s43, 0
	v_cvt_pk_bf16_f32 v62, v62, v46
	v_alignbit_b32 v62, v62, v62, v131
	global_store_dword v136, v62, s[0:1] nt
	v_max_f32_e32 v63, v63, v63
	v_max_f32_e32 v47, v47, v47
	v_max_f32_e32 v63, 0, v63
	v_max_f32_e32 v47, 0, v47
	v_mul_f32_e32 v63, v63, v63
	v_mul_f32_e32 v47, v47, v47
	s_add_u32 s0, s42, 0xb6000
	s_addc_u32 s1, s43, 0
	v_cvt_pk_bf16_f32 v63, v63, v47
	v_alignbit_b32 v63, v63, v63, v131
	global_store_dword v136, v63, s[0:1] nt
	v_max_f32_e32 v16, v16, v16
	v_max_f32_e32 v0, v0, v0
	v_max_f32_e32 v16, 0, v16
	v_max_f32_e32 v0, 0, v0
	v_mul_f32_e32 v16, v16, v16
	v_mul_f32_e32 v0, v0, v0
	s_add_u32 s0, s42, 0xc0000
	s_addc_u32 s1, s43, 0
	v_cvt_pk_bf16_f32 v16, v16, v0
	v_alignbit_b32 v16, v16, v16, v131
	global_store_dword v136, v16, s[0:1] nt
	v_max_f32_e32 v17, v17, v17
	v_max_f32_e32 v1, v1, v1
	v_max_f32_e32 v17, 0, v17
	v_max_f32_e32 v1, 0, v1
	v_mul_f32_e32 v17, v17, v17
	v_mul_f32_e32 v1, v1, v1
	s_add_u32 s0, s42, 0xc2000
	s_addc_u32 s1, s43, 0
	v_cvt_pk_bf16_f32 v17, v17, v1
	v_alignbit_b32 v17, v17, v17, v131
	global_store_dword v136, v17, s[0:1] nt
	v_max_f32_e32 v18, v18, v18
	v_max_f32_e32 v2, v2, v2
	v_max_f32_e32 v18, 0, v18
	v_max_f32_e32 v2, 0, v2
	v_mul_f32_e32 v18, v18, v18
	v_mul_f32_e32 v2, v2, v2
	s_add_u32 s0, s42, 0xc4000
	s_addc_u32 s1, s43, 0
	v_cvt_pk_bf16_f32 v18, v18, v2
	v_alignbit_b32 v18, v18, v18, v131
	global_store_dword v136, v18, s[0:1] nt
	v_max_f32_e32 v19, v19, v19
	v_max_f32_e32 v3, v3, v3
	v_max_f32_e32 v19, 0, v19
	v_max_f32_e32 v3, 0, v3
	v_mul_f32_e32 v19, v19, v19
	v_mul_f32_e32 v3, v3, v3
	s_add_u32 s0, s42, 0xc6000
	s_addc_u32 s1, s43, 0
	v_cvt_pk_bf16_f32 v19, v19, v3
	v_alignbit_b32 v19, v19, v19, v131
	global_store_dword v136, v19, s[0:1] nt
	v_max_f32_e32 v20, v20, v20
	v_max_f32_e32 v4, v4, v4
	v_max_f32_e32 v20, 0, v20
	v_max_f32_e32 v4, 0, v4
	v_mul_f32_e32 v20, v20, v20
	v_mul_f32_e32 v4, v4, v4
	s_add_u32 s0, s42, 0xd0000
	s_addc_u32 s1, s43, 0
	v_cvt_pk_bf16_f32 v20, v20, v4
	v_alignbit_b32 v20, v20, v20, v131
	global_store_dword v136, v20, s[0:1] nt
	v_max_f32_e32 v21, v21, v21
	v_max_f32_e32 v5, v5, v5
	v_max_f32_e32 v21, 0, v21
	v_max_f32_e32 v5, 0, v5
	v_mul_f32_e32 v21, v21, v21
	v_mul_f32_e32 v5, v5, v5
	s_add_u32 s0, s42, 0xd2000
	s_addc_u32 s1, s43, 0
	v_cvt_pk_bf16_f32 v21, v21, v5
	v_alignbit_b32 v21, v21, v21, v131
	global_store_dword v136, v21, s[0:1] nt
	v_max_f32_e32 v22, v22, v22
	v_max_f32_e32 v6, v6, v6
	v_max_f32_e32 v22, 0, v22
	v_max_f32_e32 v6, 0, v6
	v_mul_f32_e32 v22, v22, v22
	v_mul_f32_e32 v6, v6, v6
	s_add_u32 s0, s42, 0xd4000
	s_addc_u32 s1, s43, 0
	v_cvt_pk_bf16_f32 v22, v22, v6
	v_alignbit_b32 v22, v22, v22, v131
	global_store_dword v136, v22, s[0:1] nt
	v_max_f32_e32 v23, v23, v23
	v_max_f32_e32 v7, v7, v7
	v_max_f32_e32 v23, 0, v23
	v_max_f32_e32 v7, 0, v7
	v_mul_f32_e32 v23, v23, v23
	v_mul_f32_e32 v7, v7, v7
	s_add_u32 s0, s42, 0xd6000
	s_addc_u32 s1, s43, 0
	v_cvt_pk_bf16_f32 v23, v23, v7
	v_alignbit_b32 v23, v23, v23, v131
	global_store_dword v136, v23, s[0:1] nt
	v_max_f32_e32 v24, v24, v24
	v_max_f32_e32 v8, v8, v8
	v_max_f32_e32 v24, 0, v24
	v_max_f32_e32 v8, 0, v8
	v_mul_f32_e32 v24, v24, v24
	v_mul_f32_e32 v8, v8, v8
	s_add_u32 s0, s42, 0xe0000
	s_addc_u32 s1, s43, 0
	v_cvt_pk_bf16_f32 v24, v24, v8
	v_alignbit_b32 v24, v24, v24, v131
	global_store_dword v136, v24, s[0:1] nt
	v_max_f32_e32 v25, v25, v25
	v_max_f32_e32 v9, v9, v9
	v_max_f32_e32 v25, 0, v25
	v_max_f32_e32 v9, 0, v9
	v_mul_f32_e32 v25, v25, v25
	v_mul_f32_e32 v9, v9, v9
	s_add_u32 s0, s42, 0xe2000
	s_addc_u32 s1, s43, 0
	v_cvt_pk_bf16_f32 v25, v25, v9
	v_alignbit_b32 v25, v25, v25, v131
	global_store_dword v136, v25, s[0:1] nt
	v_max_f32_e32 v26, v26, v26
	v_max_f32_e32 v10, v10, v10
	v_max_f32_e32 v26, 0, v26
	v_max_f32_e32 v10, 0, v10
	v_mul_f32_e32 v26, v26, v26
	v_mul_f32_e32 v10, v10, v10
	s_add_u32 s0, s42, 0xe4000
	s_addc_u32 s1, s43, 0
	v_cvt_pk_bf16_f32 v26, v26, v10
	v_alignbit_b32 v26, v26, v26, v131
	global_store_dword v136, v26, s[0:1] nt
	v_max_f32_e32 v27, v27, v27
	v_max_f32_e32 v11, v11, v11
	v_max_f32_e32 v27, 0, v27
	v_max_f32_e32 v11, 0, v11
	v_mul_f32_e32 v27, v27, v27
	v_mul_f32_e32 v11, v11, v11
	s_add_u32 s0, s42, 0xe6000
	s_addc_u32 s1, s43, 0
	v_cvt_pk_bf16_f32 v27, v27, v11
	v_alignbit_b32 v27, v27, v27, v131
	global_store_dword v136, v27, s[0:1] nt
	v_max_f32_e32 v28, v28, v28
	v_max_f32_e32 v12, v12, v12
	v_max_f32_e32 v28, 0, v28
	v_max_f32_e32 v12, 0, v12
	v_mul_f32_e32 v28, v28, v28
	v_mul_f32_e32 v12, v12, v12
	s_add_u32 s0, s42, 0xf0000
	s_addc_u32 s1, s43, 0
	v_cvt_pk_bf16_f32 v28, v28, v12
	v_alignbit_b32 v28, v28, v28, v131
	global_store_dword v136, v28, s[0:1] nt
	v_max_f32_e32 v29, v29, v29
	v_max_f32_e32 v13, v13, v13
	v_max_f32_e32 v29, 0, v29
	v_max_f32_e32 v13, 0, v13
	v_mul_f32_e32 v29, v29, v29
	v_mul_f32_e32 v13, v13, v13
	s_add_u32 s0, s42, 0xf2000
	s_addc_u32 s1, s43, 0
	v_cvt_pk_bf16_f32 v29, v29, v13
	v_alignbit_b32 v29, v29, v29, v131
	global_store_dword v136, v29, s[0:1] nt
	v_max_f32_e32 v30, v30, v30
	v_max_f32_e32 v14, v14, v14
	v_max_f32_e32 v30, 0, v30
	v_max_f32_e32 v14, 0, v14
	v_mul_f32_e32 v30, v30, v30
	v_mul_f32_e32 v14, v14, v14
	s_add_u32 s0, s42, 0xf4000
	s_addc_u32 s1, s43, 0
	v_cvt_pk_bf16_f32 v30, v30, v14
	v_alignbit_b32 v30, v30, v30, v131
	global_store_dword v136, v30, s[0:1] nt
	v_max_f32_e32 v31, v31, v31
	v_max_f32_e32 v15, v15, v15
	v_max_f32_e32 v31, 0, v31
	v_max_f32_e32 v15, 0, v15
	v_mul_f32_e32 v31, v31, v31
	v_mul_f32_e32 v15, v15, v15
	s_add_u32 s0, s42, 0xf6000
	s_addc_u32 s1, s43, 0
	v_cvt_pk_bf16_f32 v31, v31, v15
	v_alignbit_b32 v31, v31, v31, v131
	global_store_dword v136, v31, s[0:1] nt
	s_andn2_b64 exec, exec, s[48:49]
	s_cbranch_execz .LBB0_254
